# barrier wait: two release polls in flight half a round trip apart, invalidate issued at detection
# baseline (speedup 1.0000x reference)
; __device__ __forceinline__ unsigned xb_ld(unsigned* p)              { return __hip_atomic_load(p, __ATOMIC_RELAXED, __HIP_MEMORY_SCOPE_AGENT); }
; __device__ __forceinline__ unsigned xb_add(unsigned* p, unsigned v) { return __hip_atomic_fetch_add(p, v, __ATOMIC_RELAXED, __HIP_MEMORY_SCOPE_AGENT); }
; #define XB_SPIN(cond, bar) do { unsigned _sp = 0; while (cond) { __builtin_amdgcn_s_sleep(1); \
;     if ((++_sp & 255u) == 0u) { if (xb_ld(&(bar)[XB_TMO])) break; if (_sp > XB_SPIN_CAP) { atomicAdd(&(bar)[XB_TMO], 1u); break; } } } } while (0)
; __device__ __forceinline__ void xcd_barrier(const XcdBarrier& b) {
;     ...
;         const unsigned old = xb_add(&bar[XB_XSUB(b.x)], 1u);
;         const unsigned gen = old / nloc;
;         if (old + 1u == (gen + 1u) * nloc) {
;             __builtin_amdgcn_fence(__ATOMIC_RELEASE, "agent");
;             asm volatile("s_waitcnt vmcnt(0)" ::: "memory");
;             const unsigned og = xb_add(&bar[XB_TOP], 1u);
;             const unsigned tg = og / nx;
;             if (og + 1u == (tg + 1u) * nx) xb_add(&bar[XB_TOPGEN], 1u);
;             else XB_SPIN(xb_ld(&bar[XB_TOPGEN]) == tg, bar);
;             __builtin_amdgcn_fence(__ATOMIC_ACQUIRE, "agent");
;             xb_add(&bar[XB_XGEN(b.x)], 1u);
;             asm volatile("s_waitcnt vmcnt(0)" ::: "memory");
;         } else {
;             XB_SPIN(xb_ld(&bar[XB_XGEN(b.x)]) == gen, bar);
;             __builtin_amdgcn_fence(__ATOMIC_ACQUIRE, "agent");
;             asm volatile("s_waitcnt vmcnt(0)" ::: "memory");
;         }
.LBB0_43:
	s_or_b64 exec, exec, s[8:9]
	v_cvt_f32_u32_e32 v5, v3
	s_waitcnt vmcnt(0)
	v_readfirstlane_b32 s6, v4
	v_sub_u32_e32 v4, 0, v3
	v_rcp_iflag_f32_e32 v5, v5
	v_add_u32_e32 v6, s6, v2
	v_mul_f32_e32 v5, 0x4f7ffffe, v5
	v_cvt_u32_f32_e32 v5, v5
	v_mul_lo_u32 v2, v4, v5
	v_mul_hi_u32 v2, v5, v2
	v_add_u32_e32 v2, v5, v2
	v_mul_hi_u32 v2, v6, v2
	v_mul_lo_u32 v4, v2, v3
	v_sub_u32_e32 v4, v6, v4
	v_add_u32_e32 v5, 1, v2
	v_cmp_ge_u32_e32 vcc, v4, v3
	s_nop 1
	v_cndmask_b32_e32 v2, v2, v5, vcc
	v_sub_u32_e32 v5, v4, v3
	v_cndmask_b32_e32 v4, v4, v5, vcc
	v_add_u32_e32 v5, 1, v2
	v_cmp_ge_u32_e32 vcc, v4, v3
	v_add_u32_e32 v4, 1, v6
	s_nop 0
	v_cndmask_b32_e32 v2, v2, v5, vcc
	v_mul_lo_u32 v5, v3, v2
	v_add_u32_e32 v3, v5, v3
	v_cmp_ne_u32_e32 vcc, v4, v3
	s_and_saveexec_b64 s[6:7], vcc
	s_xor_b64 s[6:7], exec, s[6:7]
	s_cbranch_execz .LBB0_57
	s_waitcnt lgkmcnt(0)
	v_mov_b32_e32 v1, 0x2000
	global_load_dword v1, v1, s[4:5] offset:1024 sc1
	s_add_u32 s12, s4, 0x2400
	s_addc_u32 s13, s5, 0
	s_waitcnt vmcnt(0)
	v_cmp_eq_u32_e32 vcc, v1, v2
	s_and_saveexec_b64 s[8:9], vcc
	s_cbranch_execz .LBB0_56
	v_mov_b32_e32 v5, 0x2000
	s_movk_i32 s24, 0x1000
	global_load_dword v6, v5, s[4:5] offset:1024 sc1
	s_sleep 12
	s_branch .Lxb_pl_9
.Lxb_px_9:
	buffer_inv sc1
	s_or_b64 exec, exec, s[8:9]
	s_waitcnt vmcnt(0)
	s_branch .LBB0_57
.Lxb_pl_9:
	global_load_dword v1, v5, s[4:5] offset:1024 sc1
	s_waitcnt vmcnt(1)
	v_cmp_ne_u32_e32 vcc, v6, v2
	s_cbranch_vccnz .Lxb_px_9
	global_load_dword v6, v5, s[4:5] offset:1024 sc1
	s_waitcnt vmcnt(1)
	v_cmp_ne_u32_e32 vcc, v1, v2
	s_cbranch_vccnz .Lxb_px_9
	s_add_i32 s24, s24, -1
	s_cmp_lg_u32 s24, 0
	s_cbranch_scc1 .Lxb_pl_9
	s_waitcnt vmcnt(0)
	s_add_u32 s10, s2, 0x1200
	s_addc_u32 s11, s3, 0
	s_mov_b32 s24, 1
	s_mov_b64 s[14:15], 0
	v_mov_b32_e32 v1, 0
	s_branch .LBB0_47

; __device__ __forceinline__ unsigned xb_ld(unsigned* p)              { return __hip_atomic_load(p, __ATOMIC_RELAXED, __HIP_MEMORY_SCOPE_AGENT); }
; __device__ __forceinline__ unsigned xb_add(unsigned* p, unsigned v) { return __hip_atomic_fetch_add(p, v, __ATOMIC_RELAXED, __HIP_MEMORY_SCOPE_AGENT); }
; #define XB_SPIN(cond, bar) do { unsigned _sp = 0; while (cond) { __builtin_amdgcn_s_sleep(1); \
;     if ((++_sp & 255u) == 0u) { if (xb_ld(&(bar)[XB_TMO])) break; if (_sp > XB_SPIN_CAP) { atomicAdd(&(bar)[XB_TMO], 1u); break; } } } } while (0)
; __device__ __forceinline__ void xcd_barrier(const XcdBarrier& b) {
;     ...
;         if (old + 1u == (gen + 1u) * nloc) {
;             __builtin_amdgcn_fence(__ATOMIC_RELEASE, "agent");
;             asm volatile("s_waitcnt vmcnt(0)" ::: "memory");
;             const unsigned og = xb_add(&bar[XB_TOP], 1u);
;             const unsigned tg = og / nx;
;             if (og + 1u == (tg + 1u) * nx) xb_add(&bar[XB_TOPGEN], 1u);
;             else XB_SPIN(xb_ld(&bar[XB_TOPGEN]) == tg, bar);
;             __builtin_amdgcn_fence(__ATOMIC_ACQUIRE, "agent");
.LBB0_60:
	s_or_b64 exec, exec, s[8:9]
	v_cvt_f32_u32_e32 v4, v1
	s_waitcnt vmcnt(0)
	v_readfirstlane_b32 s6, v3
	s_add_u32 s8, s2, 0x4500
	s_addc_u32 s9, s3, 0
	v_rcp_iflag_f32_e32 v4, v4
	v_add_u32_e32 v2, s6, v2
	v_add_u32_e32 v5, 1, v2
	s_mov_b64 s[10:11], -1
	v_mul_f32_e32 v3, 0x4f7ffffe, v4
	v_cvt_u32_f32_e32 v3, v3
	v_sub_u32_e32 v4, 0, v1
	v_mul_lo_u32 v4, v4, v3
	v_mul_hi_u32 v4, v3, v4
	v_add_u32_e32 v3, v3, v4
	v_mul_hi_u32 v3, v2, v3
	v_mul_lo_u32 v4, v3, v1
	v_sub_u32_e32 v2, v2, v4
	v_add_u32_e32 v6, 1, v3
	v_cmp_ge_u32_e32 vcc, v2, v1
	v_sub_u32_e32 v4, v2, v1
	s_nop 0
	v_cndmask_b32_e32 v3, v3, v6, vcc
	v_cndmask_b32_e32 v2, v2, v4, vcc
	v_add_u32_e32 v4, 1, v3
	v_cmp_ge_u32_e32 vcc, v2, v1
	s_nop 1
	v_cndmask_b32_e32 v4, v3, v4, vcc
	v_mul_lo_u32 v2, v1, v4
	v_add_u32_e32 v1, v2, v1
	v_cmp_ne_u32_e32 vcc, v5, v1
	v_mov_b64_e32 v[2:3], s[8:9]
	s_and_saveexec_b64 s[6:7], vcc
	s_cbranch_execz .Lxb_last_9
	s_add_u32 s8, s4, 0x2400
	s_addc_u32 s9, s5, 0
	v_mov_b32_e32 v1, 0
	global_load_dword v2, v1, s[8:9] sc1
	s_mov_b64 s[14:15], 0
	s_waitcnt vmcnt(0)
	v_cmp_eq_u32_e32 vcc, v2, v4
	s_and_saveexec_b64 s[12:13], vcc
	s_cbranch_execz .LBB0_71
	s_movk_i32 s22, 0x1000
	global_load_dword v6, v1, s[8:9] sc1
	s_sleep 12
	s_branch .Lxb_ql_9
.Lxb_qx_9:
	buffer_inv sc1
	s_waitcnt vmcnt(0)
	s_branch .LBB0_77
.Lxb_ql_9:
	global_load_dword v5, v1, s[8:9] sc1
	s_waitcnt vmcnt(1)
	v_cmp_ne_u32_e32 vcc, v6, v4
	s_cbranch_vccnz .Lxb_qx_9
	global_load_dword v6, v1, s[8:9] sc1
	s_waitcnt vmcnt(1)
	v_cmp_ne_u32_e32 vcc, v5, v4
	s_cbranch_vccnz .Lxb_qx_9
	s_add_i32 s22, s22, -1
	s_cmp_lg_u32 s22, 0
	s_cbranch_scc1 .Lxb_ql_9
	s_waitcnt vmcnt(0)
	s_add_u32 s10, s2, 0x1200
	s_addc_u32 s11, s3, 0
	s_mov_b32 s22, 1
	s_mov_b64 s[2:3], 0
	s_branch .LBB0_64

; __device__ __forceinline__ unsigned xb_ld(unsigned* p)              { return __hip_atomic_load(p, __ATOMIC_RELAXED, __HIP_MEMORY_SCOPE_AGENT); }
; __device__ __forceinline__ unsigned xb_add(unsigned* p, unsigned v) { return __hip_atomic_fetch_add(p, v, __ATOMIC_RELAXED, __HIP_MEMORY_SCOPE_AGENT); }
; #define XB_SPIN(cond, bar) do { unsigned _sp = 0; while (cond) { __builtin_amdgcn_s_sleep(1); \
;     if ((++_sp & 255u) == 0u) { if (xb_ld(&(bar)[XB_TMO])) break; if (_sp > XB_SPIN_CAP) { atomicAdd(&(bar)[XB_TMO], 1u); break; } } } } while (0)
; __device__ __forceinline__ void xcd_barrier(const XcdBarrier& b) {
;     ...
;         const unsigned old = xb_add(&bar[XB_XSUB(b.x)], 1u);
;         const unsigned gen = old / nloc;
;         if (old + 1u == (gen + 1u) * nloc) {
;             __builtin_amdgcn_fence(__ATOMIC_RELEASE, "agent");
;             asm volatile("s_waitcnt vmcnt(0)" ::: "memory");
;             const unsigned og = xb_add(&bar[XB_TOP], 1u);
;             const unsigned tg = og / nx;
;             if (og + 1u == (tg + 1u) * nx) xb_add(&bar[XB_TOPGEN], 1u);
;             else XB_SPIN(xb_ld(&bar[XB_TOPGEN]) == tg, bar);
;             __builtin_amdgcn_fence(__ATOMIC_ACQUIRE, "agent");
;             xb_add(&bar[XB_XGEN(b.x)], 1u);
;             asm volatile("s_waitcnt vmcnt(0)" ::: "memory");
;         } else {
;             XB_SPIN(xb_ld(&bar[XB_XGEN(b.x)]) == gen, bar);
.LBB0_137:
	s_or_b64 exec, exec, s[8:9]
	v_cvt_f32_u32_e32 v6, v4
	s_waitcnt vmcnt(0)
	v_readfirstlane_b32 s6, v5
	v_sub_u32_e32 v5, 0, v4
	v_rcp_iflag_f32_e32 v6, v6
	v_add_u32_e32 v7, s6, v3
	v_mul_f32_e32 v6, 0x4f7ffffe, v6
	v_cvt_u32_f32_e32 v6, v6
	v_mul_lo_u32 v3, v5, v6
	v_mul_hi_u32 v3, v6, v3
	v_add_u32_e32 v3, v6, v3
	v_mul_hi_u32 v3, v7, v3
	v_mul_lo_u32 v5, v3, v4
	v_sub_u32_e32 v5, v7, v5
	v_add_u32_e32 v6, 1, v3
	v_cmp_ge_u32_e32 vcc, v5, v4
	s_nop 1
	v_cndmask_b32_e32 v3, v3, v6, vcc
	v_sub_u32_e32 v6, v5, v4
	v_cndmask_b32_e32 v5, v5, v6, vcc
	v_add_u32_e32 v6, 1, v3
	v_cmp_ge_u32_e32 vcc, v5, v4
	v_add_u32_e32 v5, 1, v7
	s_nop 0
	v_cndmask_b32_e32 v3, v3, v6, vcc
	v_mul_lo_u32 v6, v4, v3
	v_add_u32_e32 v4, v6, v4
	v_cmp_ne_u32_e32 vcc, v5, v4
	s_and_saveexec_b64 s[6:7], vcc
	s_xor_b64 s[6:7], exec, s[6:7]
	s_cbranch_execz .LBB0_151
	s_waitcnt lgkmcnt(0)
	v_mov_b32_e32 v2, 0x2000
	global_load_dword v2, v2, s[4:5] offset:1024 sc1
	s_add_u32 s12, s4, 0x2400
	s_addc_u32 s13, s5, 0
	s_waitcnt vmcnt(0)
	v_cmp_eq_u32_e32 vcc, v2, v3
	s_and_saveexec_b64 s[8:9], vcc
	s_cbranch_execz .LBB0_150
	v_mov_b32_e32 v5, 0x2000
	s_movk_i32 s26, 0x1000
	global_load_dword v6, v5, s[4:5] offset:1024 sc1
	s_sleep 12
	s_branch .Lxb_pl_8

; __device__ __forceinline__ unsigned xb_ld(unsigned* p)              { return __hip_atomic_load(p, __ATOMIC_RELAXED, __HIP_MEMORY_SCOPE_AGENT); }
; #define XB_SPIN(cond, bar) do { unsigned _sp = 0; while (cond) { __builtin_amdgcn_s_sleep(1); \
;     if ((++_sp & 255u) == 0u) { if (xb_ld(&(bar)[XB_TMO])) break; if (_sp > XB_SPIN_CAP) { atomicAdd(&(bar)[XB_TMO], 1u); break; } } } } while (0)
; __device__ __forceinline__ void xcd_barrier(const XcdBarrier& b) {
;     ...
;             XB_SPIN(xb_ld(&bar[XB_XGEN(b.x)]) == gen, bar);
.Lxb_pl_8:
	global_load_dword v2, v5, s[4:5] offset:1024 sc1
	s_waitcnt vmcnt(1)
	v_cmp_ne_u32_e32 vcc, v6, v3
	s_cbranch_vccnz .Lxb_px_8
	global_load_dword v6, v5, s[4:5] offset:1024 sc1
	s_waitcnt vmcnt(1)
	v_cmp_ne_u32_e32 vcc, v2, v3
	s_cbranch_vccnz .Lxb_px_8
	s_add_i32 s26, s26, -1
	s_cmp_lg_u32 s26, 0
	s_cbranch_scc1 .Lxb_pl_8
	s_waitcnt vmcnt(0)
	s_add_u32 s10, s2, 0x1200
	s_addc_u32 s11, s3, 0
	s_mov_b32 s26, 1
	s_mov_b64 s[16:17], 0
	s_branch .LBB0_141

; __device__ __forceinline__ unsigned xb_ld(unsigned* p)              { return __hip_atomic_load(p, __ATOMIC_RELAXED, __HIP_MEMORY_SCOPE_AGENT); }
; __device__ __forceinline__ unsigned xb_add(unsigned* p, unsigned v) { return __hip_atomic_fetch_add(p, v, __ATOMIC_RELAXED, __HIP_MEMORY_SCOPE_AGENT); }
; #define XB_SPIN(cond, bar) do { unsigned _sp = 0; while (cond) { __builtin_amdgcn_s_sleep(1); \
;     if ((++_sp & 255u) == 0u) { if (xb_ld(&(bar)[XB_TMO])) break; if (_sp > XB_SPIN_CAP) { atomicAdd(&(bar)[XB_TMO], 1u); break; } } } } while (0)
; __device__ __forceinline__ void xcd_barrier(const XcdBarrier& b) {
;     ...
;         if (old + 1u == (gen + 1u) * nloc) {
;             __builtin_amdgcn_fence(__ATOMIC_RELEASE, "agent");
;             asm volatile("s_waitcnt vmcnt(0)" ::: "memory");
;             const unsigned og = xb_add(&bar[XB_TOP], 1u);
;             const unsigned tg = og / nx;
;             if (og + 1u == (tg + 1u) * nx) xb_add(&bar[XB_TOPGEN], 1u);
;             else XB_SPIN(xb_ld(&bar[XB_TOPGEN]) == tg, bar);
;             __builtin_amdgcn_fence(__ATOMIC_ACQUIRE, "agent");
.LBB0_154:
	s_or_b64 exec, exec, s[10:11]
	v_cvt_f32_u32_e32 v5, v2
	s_waitcnt vmcnt(0)
	v_readfirstlane_b32 s8, v4
	s_mov_b64 s[12:13], -1
	v_rcp_iflag_f32_e32 v5, v5
	v_add_u32_e32 v3, s8, v3
	v_add_u32_e32 v6, 1, v3
	s_add_u32 s8, s2, 0x4500
	v_mul_f32_e32 v4, 0x4f7ffffe, v5
	v_cvt_u32_f32_e32 v4, v4
	v_sub_u32_e32 v5, 0, v2
	s_addc_u32 s9, s3, 0
	v_mul_lo_u32 v5, v5, v4
	v_mul_hi_u32 v5, v4, v5
	v_add_u32_e32 v4, v4, v5
	v_mul_hi_u32 v4, v3, v4
	v_mul_lo_u32 v5, v4, v2
	v_sub_u32_e32 v3, v3, v5
	v_add_u32_e32 v7, 1, v4
	v_cmp_ge_u32_e32 vcc, v3, v2
	v_sub_u32_e32 v5, v3, v2
	s_nop 0
	v_cndmask_b32_e32 v4, v4, v7, vcc
	v_cndmask_b32_e32 v3, v3, v5, vcc
	v_add_u32_e32 v5, 1, v4
	v_cmp_ge_u32_e32 vcc, v3, v2
	s_nop 1
	v_cndmask_b32_e32 v4, v4, v5, vcc
	v_mul_lo_u32 v3, v2, v4
	v_add_u32_e32 v2, v3, v2
	v_cmp_ne_u32_e32 vcc, v6, v2
	v_mov_b64_e32 v[2:3], s[8:9]
	s_and_saveexec_b64 s[10:11], vcc
	s_cbranch_execz .Lxb_last_8
	s_add_u32 s8, s4, 0x2400
	s_addc_u32 s9, s5, 0
	global_load_dword v2, v35, s[8:9] sc1
	s_mov_b64 s[18:19], 0
	s_waitcnt vmcnt(0)
	v_cmp_eq_u32_e32 vcc, v2, v4
	s_and_saveexec_b64 s[16:17], vcc
	s_cbranch_execz .LBB0_165
	s_movk_i32 s26, 0x1000
	global_load_dword v6, v35, s[8:9] sc1
	s_sleep 12
	s_branch .Lxb_ql_8

; __device__ __forceinline__ unsigned xb_ld(unsigned* p)              { return __hip_atomic_load(p, __ATOMIC_RELAXED, __HIP_MEMORY_SCOPE_AGENT); }
; #define XB_SPIN(cond, bar) do { unsigned _sp = 0; while (cond) { __builtin_amdgcn_s_sleep(1); \
;     if ((++_sp & 255u) == 0u) { if (xb_ld(&(bar)[XB_TMO])) break; if (_sp > XB_SPIN_CAP) { atomicAdd(&(bar)[XB_TMO], 1u); break; } } } } while (0)
; __device__ __forceinline__ void xcd_barrier(const XcdBarrier& b) {
;     ...
;             else XB_SPIN(xb_ld(&bar[XB_TOPGEN]) == tg, bar);
.Lxb_ql_8:
	global_load_dword v5, v35, s[8:9] sc1
	s_waitcnt vmcnt(1)
	v_cmp_ne_u32_e32 vcc, v6, v4
	s_cbranch_vccnz .Lxb_qx_8
	global_load_dword v6, v35, s[8:9] sc1
	s_waitcnt vmcnt(1)
	v_cmp_ne_u32_e32 vcc, v5, v4
	s_cbranch_vccnz .Lxb_qx_8
	s_add_i32 s26, s26, -1
	s_cmp_lg_u32 s26, 0
	s_cbranch_scc1 .Lxb_ql_8
	s_waitcnt vmcnt(0)
	s_add_u32 s12, s2, 0x1200
	s_addc_u32 s13, s3, 0
	s_mov_b32 s26, 1
	s_mov_b64 s[2:3], 0
	s_branch .LBB0_158

; __device__ __forceinline__ unsigned xb_ld(unsigned* p)              { return __hip_atomic_load(p, __ATOMIC_RELAXED, __HIP_MEMORY_SCOPE_AGENT); }
; __device__ __forceinline__ unsigned xb_add(unsigned* p, unsigned v) { return __hip_atomic_fetch_add(p, v, __ATOMIC_RELAXED, __HIP_MEMORY_SCOPE_AGENT); }
; #define XB_SPIN(cond, bar) do { unsigned _sp = 0; while (cond) { __builtin_amdgcn_s_sleep(1); \
;     if ((++_sp & 255u) == 0u) { if (xb_ld(&(bar)[XB_TMO])) break; if (_sp > XB_SPIN_CAP) { atomicAdd(&(bar)[XB_TMO], 1u); break; } } } } while (0)
; __device__ __forceinline__ void xcd_barrier(const XcdBarrier& b) {
;     ...
;         const unsigned old = xb_add(&bar[XB_XSUB(b.x)], 1u);
;         const unsigned gen = old / nloc;
;         if (old + 1u == (gen + 1u) * nloc) {
;             __builtin_amdgcn_fence(__ATOMIC_RELEASE, "agent");
;             asm volatile("s_waitcnt vmcnt(0)" ::: "memory");
;             const unsigned og = xb_add(&bar[XB_TOP], 1u);
;             const unsigned tg = og / nx;
;             if (og + 1u == (tg + 1u) * nx) xb_add(&bar[XB_TOPGEN], 1u);
;             else XB_SPIN(xb_ld(&bar[XB_TOPGEN]) == tg, bar);
;             __builtin_amdgcn_fence(__ATOMIC_ACQUIRE, "agent");
;             xb_add(&bar[XB_XGEN(b.x)], 1u);
;             asm volatile("s_waitcnt vmcnt(0)" ::: "memory");
;         } else {
;             XB_SPIN(xb_ld(&bar[XB_XGEN(b.x)]) == gen, bar);
.LBB0_318:
	s_or_b64 exec, exec, s[8:9]
	v_cvt_f32_u32_e32 v6, v4
	s_waitcnt vmcnt(0)
	v_readfirstlane_b32 s6, v5
	v_sub_u32_e32 v5, 0, v4
	v_rcp_iflag_f32_e32 v6, v6
	v_add_u32_e32 v7, s6, v3
	v_mul_f32_e32 v6, 0x4f7ffffe, v6
	v_cvt_u32_f32_e32 v6, v6
	v_mul_lo_u32 v3, v5, v6
	v_mul_hi_u32 v3, v6, v3
	v_add_u32_e32 v3, v6, v3
	v_mul_hi_u32 v3, v7, v3
	v_mul_lo_u32 v5, v3, v4
	v_sub_u32_e32 v5, v7, v5
	v_add_u32_e32 v6, 1, v3
	v_cmp_ge_u32_e32 vcc, v5, v4
	s_nop 1
	v_cndmask_b32_e32 v3, v3, v6, vcc
	v_sub_u32_e32 v6, v5, v4
	v_cndmask_b32_e32 v5, v5, v6, vcc
	v_add_u32_e32 v6, 1, v3
	v_cmp_ge_u32_e32 vcc, v5, v4
	v_add_u32_e32 v5, 1, v7
	s_nop 0
	v_cndmask_b32_e32 v3, v3, v6, vcc
	v_mul_lo_u32 v6, v4, v3
	v_add_u32_e32 v4, v6, v4
	v_cmp_ne_u32_e32 vcc, v5, v4
	s_and_saveexec_b64 s[6:7], vcc
	v_readlane_b32 s46, v255, 5
	s_xor_b64 s[6:7], exec, s[6:7]
	v_readlane_b32 s47, v255, 6
	s_cbranch_execz .LBB0_332
	s_waitcnt lgkmcnt(0)
	v_mov_b32_e32 v2, 0x2000
	global_load_dword v2, v2, s[4:5] offset:1024 sc1
	s_add_u32 s12, s4, 0x2400
	s_addc_u32 s13, s5, 0
	s_waitcnt vmcnt(0)
	v_cmp_eq_u32_e32 vcc, v2, v3
	s_and_saveexec_b64 s[8:9], vcc
	s_cbranch_execz .LBB0_331
	v_mov_b32_e32 v5, 0x2000
	s_movk_i32 s24, 0x1000
	global_load_dword v6, v5, s[4:5] offset:1024 sc1
	s_sleep 12
	s_branch .Lxb_pl_6

; __device__ __forceinline__ unsigned xb_ld(unsigned* p)              { return __hip_atomic_load(p, __ATOMIC_RELAXED, __HIP_MEMORY_SCOPE_AGENT); }
; #define XB_SPIN(cond, bar) do { unsigned _sp = 0; while (cond) { __builtin_amdgcn_s_sleep(1); \
;     if ((++_sp & 255u) == 0u) { if (xb_ld(&(bar)[XB_TMO])) break; if (_sp > XB_SPIN_CAP) { atomicAdd(&(bar)[XB_TMO], 1u); break; } } } } while (0)
; __device__ __forceinline__ void xcd_barrier(const XcdBarrier& b) {
;     ...
;             XB_SPIN(xb_ld(&bar[XB_XGEN(b.x)]) == gen, bar);
.Lxb_pl_6:
	global_load_dword v2, v5, s[4:5] offset:1024 sc1
	s_waitcnt vmcnt(1)
	v_cmp_ne_u32_e32 vcc, v6, v3
	s_cbranch_vccnz .Lxb_px_6
	global_load_dword v6, v5, s[4:5] offset:1024 sc1
	s_waitcnt vmcnt(1)
	v_cmp_ne_u32_e32 vcc, v2, v3
	s_cbranch_vccnz .Lxb_px_6
	s_add_i32 s24, s24, -1
	s_cmp_lg_u32 s24, 0
	s_cbranch_scc1 .Lxb_pl_6
	s_waitcnt vmcnt(0)
	s_add_u32 s10, s2, 0x1200
	s_addc_u32 s11, s3, 0
	s_mov_b32 s24, 1
	s_mov_b64 s[14:15], 0
	s_branch .LBB0_322

; __device__ __forceinline__ unsigned xb_ld(unsigned* p)              { return __hip_atomic_load(p, __ATOMIC_RELAXED, __HIP_MEMORY_SCOPE_AGENT); }
; __device__ __forceinline__ unsigned xb_add(unsigned* p, unsigned v) { return __hip_atomic_fetch_add(p, v, __ATOMIC_RELAXED, __HIP_MEMORY_SCOPE_AGENT); }
; #define XB_SPIN(cond, bar) do { unsigned _sp = 0; while (cond) { __builtin_amdgcn_s_sleep(1); \
;     if ((++_sp & 255u) == 0u) { if (xb_ld(&(bar)[XB_TMO])) break; if (_sp > XB_SPIN_CAP) { atomicAdd(&(bar)[XB_TMO], 1u); break; } } } } while (0)
; __device__ __forceinline__ void xcd_barrier(const XcdBarrier& b) {
;     ...
;         if (old + 1u == (gen + 1u) * nloc) {
;             __builtin_amdgcn_fence(__ATOMIC_RELEASE, "agent");
;             asm volatile("s_waitcnt vmcnt(0)" ::: "memory");
;             const unsigned og = xb_add(&bar[XB_TOP], 1u);
;             const unsigned tg = og / nx;
;             if (og + 1u == (tg + 1u) * nx) xb_add(&bar[XB_TOPGEN], 1u);
;             else XB_SPIN(xb_ld(&bar[XB_TOPGEN]) == tg, bar);
;             __builtin_amdgcn_fence(__ATOMIC_ACQUIRE, "agent");
.LBB0_335:
	s_or_b64 exec, exec, s[8:9]
	s_waitcnt vmcnt(0)
	v_readfirstlane_b32 s6, v4
	v_cvt_f32_u32_e32 v4, v2
	v_sub_u32_e32 v5, 0, v2
	v_add_u32_e32 v3, s6, v3
	s_add_u32 s6, s2, 0x4500
	v_rcp_iflag_f32_e32 v4, v4
	s_addc_u32 s7, s3, 0
	s_mov_b64 s[10:11], -1
	v_mul_f32_e32 v4, 0x4f7ffffe, v4
	v_cvt_u32_f32_e32 v4, v4
	v_mul_lo_u32 v5, v5, v4
	v_mul_hi_u32 v5, v4, v5
	v_add_u32_e32 v4, v4, v5
	v_mul_hi_u32 v4, v3, v4
	v_mul_lo_u32 v5, v4, v2
	v_sub_u32_e32 v5, v3, v5
	v_cmp_ge_u32_e32 vcc, v5, v2
	v_add_u32_e32 v6, 1, v4
	v_add_u32_e32 v3, 1, v3
	v_cndmask_b32_e32 v4, v4, v6, vcc
	v_sub_u32_e32 v6, v5, v2
	v_cndmask_b32_e32 v5, v5, v6, vcc
	v_cmp_ge_u32_e32 vcc, v5, v2
	v_add_u32_e32 v5, 1, v4
	s_nop 0
	v_cndmask_b32_e32 v4, v4, v5, vcc
	v_mul_lo_u32 v5, v2, v4
	v_add_u32_e32 v2, v5, v2
	v_cmp_ne_u32_e32 vcc, v3, v2
	v_mov_b64_e32 v[2:3], s[6:7]
	s_and_saveexec_b64 s[8:9], vcc
	s_cbranch_execz .Lxb_last_6
	s_add_u32 s6, s4, 0x2400
	s_addc_u32 s7, s5, 0
	global_load_dword v2, v35, s[6:7] sc1
	s_mov_b64 s[14:15], 0
	s_waitcnt vmcnt(0)
	v_cmp_eq_u32_e32 vcc, v2, v4
	s_and_saveexec_b64 s[12:13], vcc
	s_cbranch_execz .LBB0_346
	s_movk_i32 s22, 0x1000
	global_load_dword v6, v35, s[6:7] sc1
	s_sleep 12
	s_branch .Lxb_ql_6

; __device__ __forceinline__ unsigned xb_ld(unsigned* p)              { return __hip_atomic_load(p, __ATOMIC_RELAXED, __HIP_MEMORY_SCOPE_AGENT); }
; #define XB_SPIN(cond, bar) do { unsigned _sp = 0; while (cond) { __builtin_amdgcn_s_sleep(1); \
;     if ((++_sp & 255u) == 0u) { if (xb_ld(&(bar)[XB_TMO])) break; if (_sp > XB_SPIN_CAP) { atomicAdd(&(bar)[XB_TMO], 1u); break; } } } } while (0)
; __device__ __forceinline__ void xcd_barrier(const XcdBarrier& b) {
;     ...
;             else XB_SPIN(xb_ld(&bar[XB_TOPGEN]) == tg, bar);
.Lxb_ql_6:
	global_load_dword v5, v35, s[6:7] sc1
	s_waitcnt vmcnt(1)
	v_cmp_ne_u32_e32 vcc, v6, v4
	s_cbranch_vccnz .Lxb_qx_6
	global_load_dword v6, v35, s[6:7] sc1
	s_waitcnt vmcnt(1)
	v_cmp_ne_u32_e32 vcc, v5, v4
	s_cbranch_vccnz .Lxb_qx_6
	s_add_i32 s22, s22, -1
	s_cmp_lg_u32 s22, 0
	s_cbranch_scc1 .Lxb_ql_6
	s_waitcnt vmcnt(0)
	s_add_u32 s10, s2, 0x1200
	s_addc_u32 s11, s3, 0
	s_mov_b32 s22, 1
	s_mov_b64 s[2:3], 0
	s_branch .LBB0_339

; __device__ __forceinline__ unsigned xb_ld(unsigned* p)              { return __hip_atomic_load(p, __ATOMIC_RELAXED, __HIP_MEMORY_SCOPE_AGENT); }
; __device__ __forceinline__ unsigned xb_add(unsigned* p, unsigned v) { return __hip_atomic_fetch_add(p, v, __ATOMIC_RELAXED, __HIP_MEMORY_SCOPE_AGENT); }
; #define XB_SPIN(cond, bar) do { unsigned _sp = 0; while (cond) { __builtin_amdgcn_s_sleep(1); \
;     if ((++_sp & 255u) == 0u) { if (xb_ld(&(bar)[XB_TMO])) break; if (_sp > XB_SPIN_CAP) { atomicAdd(&(bar)[XB_TMO], 1u); break; } } } } while (0)
; __device__ __forceinline__ void xcd_barrier(const XcdBarrier& b) {
;     ...
;         if (old + 1u == (gen + 1u) * nloc) {
;             __builtin_amdgcn_fence(__ATOMIC_RELEASE, "agent");
;             asm volatile("s_waitcnt vmcnt(0)" ::: "memory");
;             const unsigned og = xb_add(&bar[XB_TOP], 1u);
;             const unsigned tg = og / nx;
;             if (og + 1u == (tg + 1u) * nx) xb_add(&bar[XB_TOPGEN], 1u);
;             else XB_SPIN(xb_ld(&bar[XB_TOPGEN]) == tg, bar);
;             __builtin_amdgcn_fence(__ATOMIC_ACQUIRE, "agent");
.LBB0_658:
	s_or_b64 exec, exec, s[10:11]
	s_waitcnt vmcnt(0)
	v_readfirstlane_b32 s8, v4
	v_cvt_f32_u32_e32 v4, v2
	v_sub_u32_e32 v5, 0, v2
	v_add_u32_e32 v3, s8, v3
	s_add_u32 s8, s2, 0x4500
	v_rcp_iflag_f32_e32 v4, v4
	s_addc_u32 s9, s3, 0
	s_mov_b64 s[12:13], -1
	v_mul_f32_e32 v4, 0x4f7ffffe, v4
	v_cvt_u32_f32_e32 v4, v4
	v_mul_lo_u32 v5, v5, v4
	v_mul_hi_u32 v5, v4, v5
	v_add_u32_e32 v4, v4, v5
	v_mul_hi_u32 v4, v3, v4
	v_mul_lo_u32 v5, v4, v2
	v_sub_u32_e32 v5, v3, v5
	v_cmp_ge_u32_e32 vcc, v5, v2
	v_add_u32_e32 v6, 1, v4
	v_add_u32_e32 v3, 1, v3
	v_cndmask_b32_e32 v4, v4, v6, vcc
	v_sub_u32_e32 v6, v5, v2
	v_cndmask_b32_e32 v5, v5, v6, vcc
	v_cmp_ge_u32_e32 vcc, v5, v2
	v_add_u32_e32 v5, 1, v4
	s_nop 0
	v_cndmask_b32_e32 v4, v4, v5, vcc
	v_mul_lo_u32 v5, v2, v4
	v_add_u32_e32 v2, v5, v2
	v_cmp_ne_u32_e32 vcc, v3, v2
	v_mov_b64_e32 v[2:3], s[8:9]
	s_and_saveexec_b64 s[10:11], vcc
	s_cbranch_execz .Lxb_last_2
	s_add_u32 s8, s4, 0x2400
	s_addc_u32 s9, s5, 0
	global_load_dword v2, v35, s[8:9] sc1
	s_mov_b64 s[16:17], 0
	s_waitcnt vmcnt(0)
	v_cmp_eq_u32_e32 vcc, v2, v4
	s_and_saveexec_b64 s[14:15], vcc
	s_cbranch_execz .LBB0_669
	s_movk_i32 s24, 0x1000
	global_load_dword v6, v35, s[8:9] sc1
	s_sleep 12
	s_branch .Lxb_ql_2

; __device__ __forceinline__ unsigned xb_ld(unsigned* p)              { return __hip_atomic_load(p, __ATOMIC_RELAXED, __HIP_MEMORY_SCOPE_AGENT); }
; #define XB_SPIN(cond, bar) do { unsigned _sp = 0; while (cond) { __builtin_amdgcn_s_sleep(1); \
;     if ((++_sp & 255u) == 0u) { if (xb_ld(&(bar)[XB_TMO])) break; if (_sp > XB_SPIN_CAP) { atomicAdd(&(bar)[XB_TMO], 1u); break; } } } } while (0)
; __device__ __forceinline__ void xcd_barrier(const XcdBarrier& b) {
;     ...
;             else XB_SPIN(xb_ld(&bar[XB_TOPGEN]) == tg, bar);
.Lxb_ql_2:
	global_load_dword v5, v35, s[8:9] sc1
	s_waitcnt vmcnt(1)
	v_cmp_ne_u32_e32 vcc, v6, v4
	s_cbranch_vccnz .Lxb_qx_2
	global_load_dword v6, v35, s[8:9] sc1
	s_waitcnt vmcnt(1)
	v_cmp_ne_u32_e32 vcc, v5, v4
	s_cbranch_vccnz .Lxb_qx_2
	s_add_i32 s24, s24, -1
	s_cmp_lg_u32 s24, 0
	s_cbranch_scc1 .Lxb_ql_2
	s_waitcnt vmcnt(0)
	s_add_u32 s12, s2, 0x1200
	s_addc_u32 s13, s3, 0
	s_mov_b32 s24, 1
	s_mov_b64 s[2:3], 0
	s_branch .LBB0_662

; __device__ __forceinline__ unsigned xb_ld(unsigned* p)              { return __hip_atomic_load(p, __ATOMIC_RELAXED, __HIP_MEMORY_SCOPE_AGENT); }
; __device__ __forceinline__ unsigned xb_add(unsigned* p, unsigned v) { return __hip_atomic_fetch_add(p, v, __ATOMIC_RELAXED, __HIP_MEMORY_SCOPE_AGENT); }
; #define XB_SPIN(cond, bar) do { unsigned _sp = 0; while (cond) { __builtin_amdgcn_s_sleep(1); \
;     if ((++_sp & 255u) == 0u) { if (xb_ld(&(bar)[XB_TMO])) break; if (_sp > XB_SPIN_CAP) { atomicAdd(&(bar)[XB_TMO], 1u); break; } } } } while (0)
; __device__ __forceinline__ void xcd_barrier(const XcdBarrier& b) {
;     ...
;         const unsigned old = xb_add(&bar[XB_XSUB(b.x)], 1u);
;         const unsigned gen = old / nloc;
;         if (old + 1u == (gen + 1u) * nloc) {
;             __builtin_amdgcn_fence(__ATOMIC_RELEASE, "agent");
;             asm volatile("s_waitcnt vmcnt(0)" ::: "memory");
;             const unsigned og = xb_add(&bar[XB_TOP], 1u);
;             const unsigned tg = og / nx;
;             if (og + 1u == (tg + 1u) * nx) xb_add(&bar[XB_TOPGEN], 1u);
;             else XB_SPIN(xb_ld(&bar[XB_TOPGEN]) == tg, bar);
;             __builtin_amdgcn_fence(__ATOMIC_ACQUIRE, "agent");
;             xb_add(&bar[XB_XGEN(b.x)], 1u);
;             asm volatile("s_waitcnt vmcnt(0)" ::: "memory");
;         } else {
;             XB_SPIN(xb_ld(&bar[XB_XGEN(b.x)]) == gen, bar);
.LBB0_938:
	s_or_b64 exec, exec, s[8:9]
	v_cvt_f32_u32_e32 v6, v4
	s_waitcnt vmcnt(0)
	v_readfirstlane_b32 s6, v5
	v_sub_u32_e32 v5, 0, v4
	v_rcp_iflag_f32_e32 v6, v6
	v_add_u32_e32 v7, s6, v3
	v_mul_f32_e32 v6, 0x4f7ffffe, v6
	v_cvt_u32_f32_e32 v6, v6
	v_mul_lo_u32 v3, v5, v6
	v_mul_hi_u32 v3, v6, v3
	v_add_u32_e32 v3, v6, v3
	v_mul_hi_u32 v3, v7, v3
	v_mul_lo_u32 v5, v3, v4
	v_sub_u32_e32 v5, v7, v5
	v_add_u32_e32 v6, 1, v3
	v_cmp_ge_u32_e32 vcc, v5, v4
	s_nop 1
	v_cndmask_b32_e32 v3, v3, v6, vcc
	v_sub_u32_e32 v6, v5, v4
	v_cndmask_b32_e32 v5, v5, v6, vcc
	v_add_u32_e32 v6, 1, v3
	v_cmp_ge_u32_e32 vcc, v5, v4
	v_add_u32_e32 v5, 1, v7
	s_nop 0
	v_cndmask_b32_e32 v3, v3, v6, vcc
	v_mul_lo_u32 v6, v4, v3
	v_add_u32_e32 v4, v6, v4
	v_cmp_ne_u32_e32 vcc, v5, v4
	s_and_saveexec_b64 s[6:7], vcc
	s_xor_b64 s[6:7], exec, s[6:7]
	s_cbranch_execz .LBB0_952
	s_waitcnt lgkmcnt(0)
	v_mov_b32_e32 v2, 0x2000
	global_load_dword v2, v2, s[4:5] offset:1024 sc1
	s_add_u32 s12, s4, 0x2400
	s_addc_u32 s13, s5, 0
	s_waitcnt vmcnt(0)
	v_cmp_eq_u32_e32 vcc, v2, v3
	s_and_saveexec_b64 s[8:9], vcc
	s_cbranch_execz .LBB0_951
	v_mov_b32_e32 v5, 0x2000
	s_movk_i32 s24, 0x1000
	global_load_dword v6, v5, s[4:5] offset:1024 sc1
	s_sleep 12
	s_branch .Lxb_pl_1
